# attention output stores: permlane32_swap pairs turn the eight 8-byte row stores per unit into four 16-byte stores
# speedup vs baseline: 1.1381x; 1.0021x over previous
; DI unsigned pk2(float lo, float hi) { f32x2 v = {lo, hi}; bf16x2_t b = __builtin_convertvector(v, bf16x2_t); return __builtin_bit_cast(unsigned, b); }
; DI void attn_unit(int wv, int h, int qb, const bf16_t* QB, const bf16_t* KB, const bf16_t* VT, bf16_t* MIX, LAS unsigned char* lds) {
;     ...
;     lrun += __shfl_xor(lrun, 32);
;     const float inv = 1.f / lrun;
;     bf16_t* op = MIX + (size_t)qg * 1024 + 512 + h * 64;
; #pragma unroll
;     for (int g = 0; g < 4; ++g) { const int dv = 8 * g + 4 * hi;
;         u32x2 w; w.x = pk2(o0[4 * g] * inv, o0[4 * g + 1] * inv); w.y = pk2(o0[4 * g + 2] * inv, o0[4 * g + 3] * inv); *(u32x2*)(op + dv) = w;
;         u32x2 w2; w2.x = pk2(o1[4 * g] * inv, o1[4 * g + 1] * inv); w2.y = pk2(o1[4 * g + 2] * inv, o1[4 * g + 3] * inv); *(u32x2*)(op + 32 + dv) = w2; }
.LBB0_790:
	ds_bpermute_b32 v0, v195, v208
	v_lshlrev_b64 v[2:3], 11, v[166:167]
	v_lshl_add_u64 v[2:3], s[30:31], 0, v[2:3]
	v_lshl_add_u64 v[2:3], s[16:17], 1, v[2:3]
	s_waitcnt lgkmcnt(0)
	v_add_f32_e32 v0, v208, v0
	v_div_scale_f32 v4, s[0:1], v0, v0, 1.0
	v_rcp_f32_e32 v5, v4
	v_div_scale_f32 v7, vcc, 1.0, v0, 1.0
	v_readlane_b32 s1, v240, 17
	v_fma_f32 v8, -v4, v5, 1.0
	v_fmac_f32_e32 v5, v8, v5
	v_mul_f32_e32 v8, v7, v5
	v_fma_f32 v9, -v4, v8, v7
	v_fmac_f32_e32 v8, v9, v5
	v_fma_f32 v4, -v4, v8, v7
	v_div_fmas_f32 v4, v4, v5, v8
	v_div_fixup_f32 v0, v4, v0, 1.0
	v_mov_b32_e32 v7, v1
	v_lshl_add_u64 v[2:3], v[6:7], 2, v[2:3]
	v_pk_mul_f32 v[32:33], v[32:33], v[0:1] op_sel_hi:[1,0]
	v_pk_mul_f32 v[34:35], v[34:35], v[0:1] op_sel_hi:[1,0]
	v_pk_mul_f32 v[36:37], v[36:37], v[0:1] op_sel_hi:[1,0]
	v_pk_mul_f32 v[38:39], v[38:39], v[0:1] op_sel_hi:[1,0]
	v_cvt_pk_bf16_f32 v48, v32, v33
	v_cvt_pk_bf16_f32 v49, v34, v35
	v_cvt_pk_bf16_f32 v50, v36, v37
	v_cvt_pk_bf16_f32 v51, v38, v39
	s_nop 1
	v_permlane32_swap_b32_e32 v48, v50
	v_permlane32_swap_b32_e32 v49, v51
	global_store_dwordx4 v[2:3], v[48:51], off offset:1024
	v_pk_mul_f32 v[40:41], v[40:41], v[0:1] op_sel_hi:[1,0]
	v_pk_mul_f32 v[42:43], v[42:43], v[0:1] op_sel_hi:[1,0]
	v_pk_mul_f32 v[44:45], v[44:45], v[0:1] op_sel_hi:[1,0]
	v_pk_mul_f32 v[46:47], v[46:47], v[0:1] op_sel_hi:[1,0]
	v_cvt_pk_bf16_f32 v52, v40, v41
	v_cvt_pk_bf16_f32 v53, v42, v43
	v_cvt_pk_bf16_f32 v54, v44, v45
	v_cvt_pk_bf16_f32 v55, v46, v47
	s_nop 1
	v_permlane32_swap_b32_e32 v52, v54
	v_permlane32_swap_b32_e32 v53, v55
	global_store_dwordx4 v[2:3], v[52:55], off offset:1056
	v_pk_mul_f32 v[16:17], v[16:17], v[0:1] op_sel_hi:[1,0]
	v_pk_mul_f32 v[18:19], v[18:19], v[0:1] op_sel_hi:[1,0]
	v_pk_mul_f32 v[20:21], v[20:21], v[0:1] op_sel_hi:[1,0]
	v_pk_mul_f32 v[22:23], v[22:23], v[0:1] op_sel_hi:[1,0]
	v_cvt_pk_bf16_f32 v56, v16, v17
	v_cvt_pk_bf16_f32 v57, v18, v19
	v_cvt_pk_bf16_f32 v58, v20, v21
	v_cvt_pk_bf16_f32 v59, v22, v23
	s_nop 1
	v_permlane32_swap_b32_e32 v56, v58
	v_permlane32_swap_b32_e32 v57, v59
	global_store_dwordx4 v[2:3], v[56:59], off offset:1088
	v_pk_mul_f32 v[24:25], v[24:25], v[0:1] op_sel_hi:[1,0]
	v_pk_mul_f32 v[26:27], v[26:27], v[0:1] op_sel_hi:[1,0]
	v_pk_mul_f32 v[28:29], v[28:29], v[0:1] op_sel_hi:[1,0]
	v_pk_mul_f32 v[30:31], v[30:31], v[0:1] op_sel_hi:[1,0]
	v_cvt_pk_bf16_f32 v60, v24, v25
	v_cvt_pk_bf16_f32 v61, v26, v27
	v_cvt_pk_bf16_f32 v62, v28, v29
	v_cvt_pk_bf16_f32 v63, v30, v31
	s_nop 1
	v_permlane32_swap_b32_e32 v60, v62
	v_permlane32_swap_b32_e32 v61, v63
	global_store_dwordx4 v[2:3], v[60:63], off offset:1120
	s_barrier
	s_load_dword s0, s[88:89], 0x0
	s_waitcnt lgkmcnt(0)
	s_add_i32 s1, s0, s1
	s_cmpk_lt_i32 s1, 0x100
	s_cbranch_scc0 .LBB0_944

; DI unsigned pk2(float lo, float hi) { f32x2 v = {lo, hi}; bf16x2_t b = __builtin_convertvector(v, bf16x2_t); return __builtin_bit_cast(unsigned, b); }
; DI int ltid(int wv) { asm volatile("" : "+s"(wv)); int l = __builtin_amdgcn_mbcnt_hi(~0u, __builtin_amdgcn_mbcnt_lo(~0u, 0u)); asm volatile("" : "+v"(l)); return wv * 64 + l; }
; DI void attn_unit(int wv, int h, int qb, const bf16_t* QB, const bf16_t* KB, const bf16_t* VT, bf16_t* MIX, LAS unsigned char* lds) {
;     const int tid = ltid(wv), lane = tid & 63, r32 = lane & 31, hi = lane >> 5; const int wid = __builtin_amdgcn_readfirstlane(tid >> 6);
;     const int qg = qb * 256 + wid * 32 + r32;
;     const bf16_t* Kh = KB + (size_t)h * S * 96; const bf16_t* Vh = VT + (size_t)h * 64 * S;
;     bf16x8 qf[6];
;     { const bf16_t* qp = QB + ((size_t)h * S + qg) * 96 + 8 * hi;
; #pragma unroll
;       for (int s = 0; s < 6; ++s) qf[s] = *(const bf16x8*)(qp + 16 * s); }
;     f32x16 o0 = {}, o1 = {}, negm = {};
;     float mref = 0.f, lrun = 0.f;
;     const int NT = 4 * qb + 4, wlim = 4 * qb + (wid >> 1);
;     const int kc0 = tid, kkey0 = kc0 / 12, kpart0 = kc0 % 12;
;     const int kc1 = tid + 512, kkey1 = kc1 / 12, kpart1 = kc1 % 12;
;     const int vdv = tid >> 3, vpart = tid & 7;
;     u32x4 rk0, rk1 = {}, rv;
;     ...
;     lrun += __shfl_xor(lrun, 32);
;     const float inv = 1.f / lrun;
;     bf16_t* op = MIX + (size_t)qg * 1024 + 512 + h * 64;
; #pragma unroll
;     for (int g = 0; g < 4; ++g) { const int dv = 8 * g + 4 * hi;
;         u32x2 w; w.x = pk2(o0[4 * g] * inv, o0[4 * g + 1] * inv); w.y = pk2(o0[4 * g + 2] * inv, o0[4 * g + 3] * inv); *(u32x2*)(op + dv) = w;
;         u32x2 w2; w2.x = pk2(o1[4 * g] * inv, o1[4 * g + 1] * inv); w2.y = pk2(o1[4 * g + 2] * inv, o1[4 * g + 3] * inv); *(u32x2*)(op + 32 + dv) = w2; }
.LBB0_865:
	ds_bpermute_b32 v0, v195, v203
	v_lshlrev_b64 v[34:35], 11, v[154:155]
	s_lshl_b32 s16, s88, 6
	v_lshl_add_u64 v[34:35], s[30:31], 0, v[34:35]
	s_ashr_i32 s17, s16, 31
	s_waitcnt lgkmcnt(0)
	v_add_f32_e32 v0, v203, v0
	v_div_scale_f32 v36, s[0:1], v0, v0, 1.0
	v_rcp_f32_e32 v37, v36
	v_div_scale_f32 v38, vcc, 1.0, v0, 1.0
	v_lshl_add_u64 v[34:35], s[16:17], 1, v[34:35]
	v_fma_f32 v39, -v36, v37, 1.0
	v_fmac_f32_e32 v37, v39, v37
	v_mul_f32_e32 v39, v38, v37
	v_fma_f32 v40, -v36, v39, v38
	v_fmac_f32_e32 v39, v40, v37
	v_fma_f32 v36, -v36, v39, v38
	v_div_fmas_f32 v36, v36, v37, v39
	v_div_fixup_f32 v0, v36, v0, 1.0
	v_mov_b32_e32 v159, v1
	v_lshl_add_u64 v[36:37], v[158:159], 2, v[34:35]
	v_pk_mul_f32 v[2:3], v[2:3], v[0:1] op_sel_hi:[1,0]
	v_pk_mul_f32 v[4:5], v[4:5], v[0:1] op_sel_hi:[1,0]
	v_pk_mul_f32 v[6:7], v[6:7], v[0:1] op_sel_hi:[1,0]
	v_pk_mul_f32 v[8:9], v[8:9], v[0:1] op_sel_hi:[1,0]
	v_cvt_pk_bf16_f32 v40, v2, v3
	v_cvt_pk_bf16_f32 v41, v4, v5
	v_cvt_pk_bf16_f32 v42, v6, v7
	v_cvt_pk_bf16_f32 v43, v8, v9
	s_nop 1
	v_permlane32_swap_b32_e32 v40, v42
	v_permlane32_swap_b32_e32 v41, v43
	global_store_dwordx4 v[36:37], v[40:43], off offset:1024
	v_pk_mul_f32 v[10:11], v[10:11], v[0:1] op_sel_hi:[1,0]
	v_pk_mul_f32 v[12:13], v[12:13], v[0:1] op_sel_hi:[1,0]
	v_pk_mul_f32 v[14:15], v[14:15], v[0:1] op_sel_hi:[1,0]
	v_pk_mul_f32 v[16:17], v[16:17], v[0:1] op_sel_hi:[1,0]
	v_cvt_pk_bf16_f32 v44, v10, v11
	v_cvt_pk_bf16_f32 v45, v12, v13
	v_cvt_pk_bf16_f32 v46, v14, v15
	v_cvt_pk_bf16_f32 v47, v16, v17
	s_nop 1
	v_permlane32_swap_b32_e32 v44, v46
	v_permlane32_swap_b32_e32 v45, v47
	global_store_dwordx4 v[36:37], v[44:47], off offset:1056
	v_pk_mul_f32 v[18:19], v[18:19], v[0:1] op_sel_hi:[1,0]
	v_pk_mul_f32 v[20:21], v[20:21], v[0:1] op_sel_hi:[1,0]
	v_pk_mul_f32 v[22:23], v[22:23], v[0:1] op_sel_hi:[1,0]
	v_pk_mul_f32 v[24:25], v[24:25], v[0:1] op_sel_hi:[1,0]
	v_cvt_pk_bf16_f32 v48, v18, v19
	v_cvt_pk_bf16_f32 v49, v20, v21
	v_cvt_pk_bf16_f32 v50, v22, v23
	v_cvt_pk_bf16_f32 v51, v24, v25
	s_nop 1
	v_permlane32_swap_b32_e32 v48, v50
	v_permlane32_swap_b32_e32 v49, v51
	global_store_dwordx4 v[36:37], v[48:51], off offset:1088
	v_pk_mul_f32 v[26:27], v[26:27], v[0:1] op_sel_hi:[1,0]
	v_pk_mul_f32 v[28:29], v[28:29], v[0:1] op_sel_hi:[1,0]
	v_pk_mul_f32 v[30:31], v[30:31], v[0:1] op_sel_hi:[1,0]
	v_pk_mul_f32 v[32:33], v[32:33], v[0:1] op_sel_hi:[1,0]
	v_cvt_pk_bf16_f32 v52, v26, v27
	v_cvt_pk_bf16_f32 v53, v28, v29
	v_cvt_pk_bf16_f32 v54, v30, v31
	v_cvt_pk_bf16_f32 v55, v32, v33
	s_nop 1
	v_permlane32_swap_b32_e32 v52, v54
	v_permlane32_swap_b32_e32 v53, v55
	global_store_dwordx4 v[36:37], v[52:55], off offset:1120
	s_mov_b32 s0, s50
	v_mov_b32_e32 v9, v192
	s_barrier
	v_mov_b32_e32 v152, v1
	v_lshl_add_u32 v10, s0, 6, v9
	s_lshl_b32 s0, s5, 8
	v_readfirstlane_b32 s14, v10
	s_ashr_i32 s1, s14, 1
	s_andn2_b32 s1, s1, 31
	v_and_b32_e32 v8, 31, v9
	s_add_i32 s1, s1, s0
	v_or_b32_e32 v166, s1, v8
	v_readlane_b32 s0, v240, 18
	v_ashrrev_i32_e32 v167, 31, v166
	v_readlane_b32 s1, v240, 19
	v_bfe_u32 v187, v9, 5, 1
	v_lshlrev_b32_e32 v0, 4, v187
	v_lshl_add_u64 v[2:3], s[0:1], 0, v[166:167]
	v_readlane_b32 s0, v240, 9
	v_readlane_b32 s1, v240, 10
	v_add_u32_e32 v13, 0x200, v10
	v_mul_hi_i32 v14, v13, s35
	v_mov_b64_e32 v[4:5], s[0:1]
	v_mad_u64_u32 v[4:5], s[0:1], v2, s34, v[4:5]
	v_mad_i32_i24 v5, v3, s34, v5
	v_lshl_add_u64 v[2:3], v[4:5], 0, v[0:1]
	global_load_dwordx4 v[128:131], v[2:3], off
	global_load_dwordx4 v[132:135], v[2:3], off offset:32
	global_load_dwordx4 v[136:139], v[2:3], off offset:64
	global_load_dwordx4 v[140:143], v[2:3], off offset:96
	global_load_dwordx4 v[144:147], v[2:3], off offset:128
	global_load_dwordx4 v[148:151], v[2:3], off offset:160
	v_mul_hi_i32 v2, v10, s35
	v_lshrrev_b32_e32 v3, 31, v2
	v_ashrrev_i32_e32 v2, 1, v2
	v_add_u32_e32 v11, v2, v3
	v_mul_lo_u32 v2, v11, 12
	v_sub_u32_e32 v12, v10, v2
	v_mov_b64_e32 v[2:3], s[76:77]
	v_lshlrev_b32_e32 v170, 3, v12
	v_mad_i64_i32 v[2:3], s[0:1], v11, s34, v[2:3]
	v_ashrrev_i32_e32 v171, 31, v170
	v_lshl_add_u64 v[6:7], v[170:171], 1, v[2:3]
	global_load_dwordx4 v[2:5], v[6:7], off
	v_lshrrev_b32_e32 v15, 31, v14
	v_ashrrev_i32_e32 v14, 1, v14
	v_add_u32_e32 v186, v14, v15
	v_mul_lo_u32 v14, v186, 12
	v_sub_u32_e32 v13, v13, v14
	v_lshlrev_b32_e32 v172, 3, v13
	v_cmp_gt_i32_e64 s[6:7], s36, v10
	v_mov_b32_e32 v153, v1
	v_mov_b32_e32 v154, v1
	v_mov_b32_e32 v155, v1
	v_ashrrev_i32_e32 v173, 31, v172
	s_and_saveexec_b64 s[8:9], s[6:7]
	s_cbranch_execz .LBB0_867
	v_mov_b64_e32 v[14:15], s[76:77]
	v_mad_i64_i32 v[14:15], s[0:1], v186, s34, v[14:15]
	v_lshl_add_u64 v[14:15], v[172:173], 1, v[14:15]
	global_load_dwordx4 v[152:155], v[14:15], off
